# speedup vs baseline: 1.0015x; 1.0008x over previous
.LBB0_849:
	v_lshl_or_b32 v158, s30, 8, v164
	v_readlane_b32 s0, v253, 50
	v_ashrrev_i32_e32 v159, 31, v158
	v_readlane_b32 s1, v253, 51
	v_lshl_add_u32 v160, s29, 8, v162
	v_ashrrev_i32_e32 v161, 31, v160
	v_lshl_add_u64 v[156:157], v[158:159], 2, s[0:1]
	global_load_dwordx4 v[140:143], v[156:157], off offset:16
	global_load_dwordx4 v[144:147], v[156:157], off
	global_load_dwordx4 v[222:225], v[156:157], off offset:528
	global_load_dwordx4 v[226:229], v[156:157], off offset:512
	v_lshl_add_u32 v184, v160, 11, v158
	v_lshlrev_b32_e32 v184, 2, v184
	v_readlane_b32 s100, v253, 58
	v_readlane_b32 s101, v253, 59
	s_nop 1
	s_add_u32 s100, s100, 0x0
	s_addc_u32 s101, s101, 0
	global_load_dwordx4 v[176:179], v184, s[100:101] offset:16
	global_load_dwordx4 v[180:183], v184, s[100:101] offset:0
	global_load_dwordx4 v[188:191], v184, s[100:101] offset:528
	global_load_dwordx4 v[192:195], v184, s[100:101] offset:512
	s_add_u32 s100, s100, 0x20000
	s_addc_u32 s101, s101, 0
	global_load_dwordx4 v[196:199], v184, s[100:101] offset:16
	global_load_dwordx4 v[200:203], v184, s[100:101] offset:0
	global_load_dwordx4 v[204:207], v184, s[100:101] offset:528
	global_load_dwordx4 v[218:221], v184, s[100:101] offset:512
	v_readlane_b32 s0, v253, 58
	v_readlane_b32 s1, v253, 59
	s_mov_b64 s[18:19], 0x40000
	s_andn2_b64 vcc, exec, s[4:5]
	s_mov_b32 s44, 0x8000
	s_mov_b32 s45, 0xa000
	s_waitcnt vmcnt(0)
	v_pk_add_f32 v[148:149], v[142:143], 1.0 op_sel_hi:[1,0]
	v_pk_add_f32 v[150:151], v[140:141], 1.0 op_sel_hi:[1,0]
	v_lshlrev_b64 v[156:157], 11, v[160:161]
	v_lshl_add_u64 v[156:157], v[156:157], 0, v[158:159]
	v_lshl_add_u64 v[174:175], v[156:157], 2, s[0:1]
	v_pk_add_f32 v[152:153], v[146:147], 1.0 op_sel_hi:[1,0]
	v_pk_add_f32 v[154:155], v[144:145], 1.0 op_sel_hi:[1,0]
	v_pk_add_f32 v[144:145], v[228:229], 1.0 op_sel_hi:[1,0]
	v_pk_add_f32 v[146:147], v[226:227], 1.0 op_sel_hi:[1,0]
	v_pk_add_f32 v[140:141], v[224:225], 1.0 op_sel_hi:[1,0]
	v_pk_add_f32 v[142:143], v[222:223], 1.0 op_sel_hi:[1,0]
	v_pk_mul_f32 v[168:169], v[178:179], s[60:61] op_sel_hi:[1,0]
	v_pk_mul_f32 v[172:173], v[182:183], s[60:61] op_sel_hi:[1,0]
	v_pk_mul_f32 v[170:171], v[180:181], s[60:61] op_sel_hi:[1,0]
	v_pk_mul_f32 v[166:167], v[176:177], s[60:61] op_sel_hi:[1,0]
	v_pk_fma_f32 v[128:129], v[128:129], v[152:153], v[172:173]
	v_pk_fma_f32 v[126:127], v[126:127], v[154:155], v[170:171]
	v_pk_fma_f32 v[168:169], v[124:125], v[148:149], v[168:169]
	v_pk_fma_f32 v[124:125], v[122:123], v[150:151], v[166:167]
	v_lshlrev_b64 v[166:167], 1, v[156:157]
	v_cvt_pk_bf16_f32 v122, v126, v127
	v_cvt_pk_bf16_f32 v123, v128, v129
	v_cvt_pk_bf16_f32 v124, v124, v125
	v_cvt_pk_bf16_f32 v125, v168, v169
	v_lshl_add_u64 v[126:127], s[50:51], 0, v[166:167]
	global_store_dwordx4 v[126:127], v[122:125], off
	s_nop 0
	v_or_b32_e32 v166, 0x100, v166
	v_pk_mul_f32 v[124:125], v[190:191], s[60:61] op_sel_hi:[1,0]
	v_pk_mul_f32 v[128:129], v[194:195], s[60:61] op_sel_hi:[1,0]
	v_pk_mul_f32 v[126:127], v[192:193], s[60:61] op_sel_hi:[1,0]
	v_pk_mul_f32 v[122:123], v[188:189], s[60:61] op_sel_hi:[1,0]
	v_pk_fma_f32 v[120:121], v[120:121], v[144:145], v[128:129]
	v_pk_fma_f32 v[118:119], v[118:119], v[146:147], v[126:127]
	v_pk_fma_f32 v[124:125], v[116:117], v[140:141], v[124:125]
	v_pk_fma_f32 v[116:117], v[114:115], v[142:143], v[122:123]
	v_cvt_pk_bf16_f32 v114, v118, v119
	v_cvt_pk_bf16_f32 v115, v120, v121
	v_cvt_pk_bf16_f32 v116, v116, v117
	v_cvt_pk_bf16_f32 v117, v124, v125
	v_lshl_add_u64 v[118:119], s[50:51], 0, v[166:167]
	global_store_dwordx4 v[118:119], v[114:117], off
	s_nop 1
	v_or_b32_e32 v114, 16, v160
	v_ashrrev_i32_e32 v115, 31, v114
	v_lshlrev_b64 v[114:115], 11, v[114:115]
	v_lshl_add_u64 v[122:123], v[114:115], 0, v[158:159]
	v_lshl_add_u64 v[124:125], v[122:123], 2, s[0:1]
	v_pk_mul_f32 v[116:117], v[198:199], s[60:61] op_sel_hi:[1,0]
	v_pk_mul_f32 v[120:121], v[202:203], s[60:61] op_sel_hi:[1,0]
	v_pk_mul_f32 v[118:119], v[200:201], s[60:61] op_sel_hi:[1,0]
	v_pk_mul_f32 v[114:115], v[196:197], s[60:61] op_sel_hi:[1,0]
	v_pk_fma_f32 v[112:113], v[112:113], v[152:153], v[120:121]
	v_pk_fma_f32 v[110:111], v[110:111], v[154:155], v[118:119]
	v_pk_fma_f32 v[116:117], v[108:109], v[148:149], v[116:117]
	v_pk_fma_f32 v[108:109], v[106:107], v[150:151], v[114:115]
	v_lshlrev_b64 v[114:115], 1, v[122:123]
	v_cvt_pk_bf16_f32 v106, v110, v111
	v_cvt_pk_bf16_f32 v107, v112, v113
	v_cvt_pk_bf16_f32 v108, v108, v109
	v_cvt_pk_bf16_f32 v109, v116, v117
	v_lshl_add_u64 v[110:111], s[50:51], 0, v[114:115]
	global_store_dwordx4 v[110:111], v[106:109], off
	s_nop 0
	v_or_b32_e32 v114, 0x100, v114
	v_pk_mul_f32 v[108:109], v[206:207], s[60:61] op_sel_hi:[1,0]
	v_pk_mul_f32 v[112:113], v[220:221], s[60:61] op_sel_hi:[1,0]
	v_pk_mul_f32 v[110:111], v[218:219], s[60:61] op_sel_hi:[1,0]
	v_pk_mul_f32 v[106:107], v[204:205], s[60:61] op_sel_hi:[1,0]
	v_pk_fma_f32 v[104:105], v[104:105], v[144:145], v[112:113]
	v_pk_fma_f32 v[102:103], v[102:103], v[146:147], v[110:111]
	v_pk_fma_f32 v[108:109], v[100:101], v[140:141], v[108:109]
	v_pk_fma_f32 v[100:101], v[98:99], v[142:143], v[106:107]
	v_cvt_pk_bf16_f32 v98, v102, v103
	v_cvt_pk_bf16_f32 v99, v104, v105
	v_cvt_pk_bf16_f32 v100, v100, v101
	v_cvt_pk_bf16_f32 v101, v108, v109
	v_lshl_add_u64 v[102:103], s[50:51], 0, v[114:115]
	global_store_dwordx4 v[102:103], v[98:101], off
	s_nop 1
	v_or_b32_e32 v98, 32, v160
	v_ashrrev_i32_e32 v99, 31, v98
	v_lshlrev_b64 v[98:99], 11, v[98:99]
	v_lshl_add_u64 v[106:107], v[98:99], 0, v[158:159]
	v_lshl_add_u64 v[108:109], v[106:107], 2, s[0:1]
	v_lshlrev_b32_e32 v184, 2, v156
	v_readlane_b32 s100, v253, 58
	v_readlane_b32 s101, v253, 59
	s_nop 1
	s_add_u32 s100, s100, 0x40000
	s_addc_u32 s101, s101, 0
	global_load_dwordx4 v[176:179], v184, s[100:101] offset:16
	global_load_dwordx4 v[180:183], v184, s[100:101] offset:0
	global_load_dwordx4 v[188:191], v184, s[100:101] offset:528
	global_load_dwordx4 v[192:195], v184, s[100:101] offset:512
	s_add_u32 s100, s100, 0x20000
	s_addc_u32 s101, s101, 0
	global_load_dwordx4 v[196:199], v184, s[100:101] offset:16
	global_load_dwordx4 v[200:203], v184, s[100:101] offset:0
	global_load_dwordx4 v[204:207], v184, s[100:101] offset:528
	global_load_dwordx4 v[218:221], v184, s[100:101] offset:512
	s_waitcnt vmcnt(0)
	v_pk_mul_f32 v[100:101], v[178:179], s[60:61] op_sel_hi:[1,0]
	v_pk_mul_f32 v[104:105], v[182:183], s[60:61] op_sel_hi:[1,0]
	v_pk_mul_f32 v[102:103], v[180:181], s[60:61] op_sel_hi:[1,0]
	v_pk_mul_f32 v[98:99], v[176:177], s[60:61] op_sel_hi:[1,0]
	v_pk_fma_f32 v[96:97], v[96:97], v[152:153], v[104:105]
	v_pk_fma_f32 v[94:95], v[94:95], v[154:155], v[102:103]
	v_pk_fma_f32 v[100:101], v[92:93], v[148:149], v[100:101]
	v_pk_fma_f32 v[92:93], v[90:91], v[150:151], v[98:99]
	v_lshlrev_b64 v[98:99], 1, v[106:107]
	v_cvt_pk_bf16_f32 v90, v94, v95
	v_cvt_pk_bf16_f32 v91, v96, v97
	v_cvt_pk_bf16_f32 v92, v92, v93
	v_cvt_pk_bf16_f32 v93, v100, v101
	v_lshl_add_u64 v[94:95], s[50:51], 0, v[98:99]
	global_store_dwordx4 v[94:95], v[90:93], off
	s_nop 0
	v_or_b32_e32 v98, 0x100, v98
	v_pk_mul_f32 v[92:93], v[190:191], s[60:61] op_sel_hi:[1,0]
	v_pk_mul_f32 v[96:97], v[194:195], s[60:61] op_sel_hi:[1,0]
	v_pk_mul_f32 v[94:95], v[192:193], s[60:61] op_sel_hi:[1,0]
	v_pk_mul_f32 v[90:91], v[188:189], s[60:61] op_sel_hi:[1,0]
	v_pk_fma_f32 v[88:89], v[88:89], v[144:145], v[96:97]
	v_pk_fma_f32 v[86:87], v[86:87], v[146:147], v[94:95]
	v_pk_fma_f32 v[92:93], v[84:85], v[140:141], v[92:93]
	v_pk_fma_f32 v[84:85], v[82:83], v[142:143], v[90:91]
	v_cvt_pk_bf16_f32 v82, v86, v87
	v_cvt_pk_bf16_f32 v83, v88, v89
	v_cvt_pk_bf16_f32 v84, v84, v85
	v_cvt_pk_bf16_f32 v85, v92, v93
	v_lshl_add_u64 v[86:87], s[50:51], 0, v[98:99]
	global_store_dwordx4 v[86:87], v[82:85], off
	s_nop 1
	v_or_b32_e32 v82, 48, v160
	v_ashrrev_i32_e32 v83, 31, v82
	v_lshlrev_b64 v[82:83], 11, v[82:83]
	v_lshl_add_u64 v[90:91], v[82:83], 0, v[158:159]
	v_lshl_add_u64 v[92:93], v[90:91], 2, s[0:1]
	v_pk_mul_f32 v[84:85], v[198:199], s[60:61] op_sel_hi:[1,0]
	v_pk_mul_f32 v[88:89], v[202:203], s[60:61] op_sel_hi:[1,0]
	v_pk_mul_f32 v[86:87], v[200:201], s[60:61] op_sel_hi:[1,0]
	v_pk_mul_f32 v[82:83], v[196:197], s[60:61] op_sel_hi:[1,0]
	v_pk_fma_f32 v[80:81], v[80:81], v[152:153], v[88:89]
	v_pk_fma_f32 v[78:79], v[78:79], v[154:155], v[86:87]
	v_pk_fma_f32 v[84:85], v[76:77], v[148:149], v[84:85]
	v_pk_fma_f32 v[76:77], v[74:75], v[150:151], v[82:83]
	v_lshlrev_b64 v[82:83], 1, v[90:91]
	v_cvt_pk_bf16_f32 v74, v78, v79
	v_cvt_pk_bf16_f32 v75, v80, v81
	v_cvt_pk_bf16_f32 v76, v76, v77
	v_cvt_pk_bf16_f32 v77, v84, v85
	v_lshl_add_u64 v[78:79], s[50:51], 0, v[82:83]
	global_store_dwordx4 v[78:79], v[74:77], off
	s_nop 0
	v_or_b32_e32 v82, 0x100, v82
	v_pk_mul_f32 v[76:77], v[206:207], s[60:61] op_sel_hi:[1,0]
	v_pk_mul_f32 v[80:81], v[220:221], s[60:61] op_sel_hi:[1,0]
	v_pk_mul_f32 v[78:79], v[218:219], s[60:61] op_sel_hi:[1,0]
	v_pk_mul_f32 v[74:75], v[204:205], s[60:61] op_sel_hi:[1,0]
	v_pk_fma_f32 v[72:73], v[72:73], v[144:145], v[80:81]
	v_pk_fma_f32 v[70:71], v[70:71], v[146:147], v[78:79]
	v_pk_fma_f32 v[76:77], v[68:69], v[140:141], v[76:77]
	v_pk_fma_f32 v[68:69], v[66:67], v[142:143], v[74:75]
	v_cvt_pk_bf16_f32 v66, v70, v71
	v_cvt_pk_bf16_f32 v67, v72, v73
	v_cvt_pk_bf16_f32 v68, v68, v69
	v_cvt_pk_bf16_f32 v69, v76, v77
	v_lshl_add_u64 v[70:71], s[50:51], 0, v[82:83]
	v_lshl_add_u64 v[74:75], v[156:157], 0, s[18:19]
	global_store_dwordx4 v[70:71], v[66:69], off
	v_lshl_add_u64 v[76:77], v[74:75], 2, s[0:1]
	v_lshlrev_b32_e32 v184, 2, v156
	v_readlane_b32 s100, v253, 58
	v_readlane_b32 s101, v253, 59
	s_nop 1
	s_add_u32 s100, s100, 0x100000
	s_addc_u32 s101, s101, 0
	global_load_dwordx4 v[176:179], v184, s[100:101] offset:16
	global_load_dwordx4 v[180:183], v184, s[100:101] offset:0
	global_load_dwordx4 v[188:191], v184, s[100:101] offset:528
	global_load_dwordx4 v[192:195], v184, s[100:101] offset:512
	s_add_u32 s100, s100, 0x20000
	s_addc_u32 s101, s101, 0
	global_load_dwordx4 v[196:199], v184, s[100:101] offset:16
	global_load_dwordx4 v[200:203], v184, s[100:101] offset:0
	global_load_dwordx4 v[204:207], v184, s[100:101] offset:528
	global_load_dwordx4 v[218:221], v184, s[100:101] offset:512
	s_waitcnt vmcnt(0)
	s_mov_b64 s[18:19], 0x48000
	v_pk_mul_f32 v[68:69], v[178:179], s[60:61] op_sel_hi:[1,0]
	v_pk_mul_f32 v[72:73], v[182:183], s[60:61] op_sel_hi:[1,0]
	v_pk_mul_f32 v[70:71], v[180:181], s[60:61] op_sel_hi:[1,0]
	v_pk_mul_f32 v[66:67], v[176:177], s[60:61] op_sel_hi:[1,0]
	v_pk_fma_f32 v[64:65], v[64:65], v[152:153], v[72:73]
	v_pk_fma_f32 v[62:63], v[62:63], v[154:155], v[70:71]
	v_pk_fma_f32 v[68:69], v[60:61], v[148:149], v[68:69]
	v_pk_fma_f32 v[60:61], v[58:59], v[150:151], v[66:67]
	v_lshlrev_b64 v[66:67], 1, v[74:75]
	v_cvt_pk_bf16_f32 v58, v62, v63
	v_cvt_pk_bf16_f32 v59, v64, v65
	v_cvt_pk_bf16_f32 v60, v60, v61
	v_cvt_pk_bf16_f32 v61, v68, v69
	v_lshl_add_u64 v[62:63], s[50:51], 0, v[66:67]
	global_store_dwordx4 v[62:63], v[58:61], off
	s_nop 0
	v_or_b32_e32 v66, 0x100, v66
	v_pk_mul_f32 v[60:61], v[190:191], s[60:61] op_sel_hi:[1,0]
	v_pk_mul_f32 v[64:65], v[194:195], s[60:61] op_sel_hi:[1,0]
	v_pk_mul_f32 v[62:63], v[192:193], s[60:61] op_sel_hi:[1,0]
	v_pk_mul_f32 v[58:59], v[188:189], s[60:61] op_sel_hi:[1,0]
	v_pk_fma_f32 v[56:57], v[56:57], v[144:145], v[64:65]
	v_pk_fma_f32 v[54:55], v[54:55], v[146:147], v[62:63]
	v_pk_fma_f32 v[60:61], v[52:53], v[140:141], v[60:61]
	v_pk_fma_f32 v[52:53], v[50:51], v[142:143], v[58:59]
	v_cvt_pk_bf16_f32 v50, v54, v55
	v_cvt_pk_bf16_f32 v51, v56, v57
	v_cvt_pk_bf16_f32 v52, v52, v53
	v_cvt_pk_bf16_f32 v53, v60, v61
	v_lshl_add_u64 v[54:55], s[50:51], 0, v[66:67]
	v_lshl_add_u64 v[58:59], v[156:157], 0, s[18:19]
	global_store_dwordx4 v[54:55], v[50:53], off
	v_lshl_add_u64 v[60:61], v[58:59], 2, s[0:1]
	s_mov_b64 s[18:19], 0x50000
	v_pk_mul_f32 v[52:53], v[198:199], s[60:61] op_sel_hi:[1,0]
	v_pk_mul_f32 v[56:57], v[202:203], s[60:61] op_sel_hi:[1,0]
	v_pk_mul_f32 v[54:55], v[200:201], s[60:61] op_sel_hi:[1,0]
	v_pk_mul_f32 v[50:51], v[196:197], s[60:61] op_sel_hi:[1,0]
	v_pk_fma_f32 v[48:49], v[48:49], v[152:153], v[56:57]
	v_pk_fma_f32 v[46:47], v[46:47], v[154:155], v[54:55]
	v_pk_fma_f32 v[52:53], v[44:45], v[148:149], v[52:53]
	v_pk_fma_f32 v[44:45], v[42:43], v[150:151], v[50:51]
	v_lshlrev_b64 v[50:51], 1, v[58:59]
	v_cvt_pk_bf16_f32 v42, v46, v47
	v_cvt_pk_bf16_f32 v43, v48, v49
	v_cvt_pk_bf16_f32 v44, v44, v45
	v_cvt_pk_bf16_f32 v45, v52, v53
	v_lshl_add_u64 v[46:47], s[50:51], 0, v[50:51]
	global_store_dwordx4 v[46:47], v[42:45], off
	s_nop 0
	v_or_b32_e32 v50, 0x100, v50
	v_pk_mul_f32 v[44:45], v[206:207], s[60:61] op_sel_hi:[1,0]
	v_pk_mul_f32 v[48:49], v[220:221], s[60:61] op_sel_hi:[1,0]
	v_pk_mul_f32 v[46:47], v[218:219], s[60:61] op_sel_hi:[1,0]
	v_pk_mul_f32 v[42:43], v[204:205], s[60:61] op_sel_hi:[1,0]
	v_pk_fma_f32 v[40:41], v[40:41], v[144:145], v[48:49]
	v_pk_fma_f32 v[38:39], v[38:39], v[146:147], v[46:47]
	v_pk_fma_f32 v[44:45], v[36:37], v[140:141], v[44:45]
	v_pk_fma_f32 v[36:37], v[34:35], v[142:143], v[42:43]
	v_cvt_pk_bf16_f32 v34, v38, v39
	v_cvt_pk_bf16_f32 v35, v40, v41
	v_cvt_pk_bf16_f32 v36, v36, v37
	v_cvt_pk_bf16_f32 v37, v44, v45
	v_lshl_add_u64 v[38:39], s[50:51], 0, v[50:51]
	v_lshl_add_u64 v[42:43], v[156:157], 0, s[18:19]
	global_store_dwordx4 v[38:39], v[34:37], off
	v_lshl_add_u64 v[44:45], v[42:43], 2, s[0:1]
	v_lshlrev_b32_e32 v184, 2, v156
	v_readlane_b32 s100, v253, 58
	v_readlane_b32 s101, v253, 59
	s_nop 1
	s_add_u32 s100, s100, 0x140000
	s_addc_u32 s101, s101, 0
	global_load_dwordx4 v[176:179], v184, s[100:101] offset:16
	global_load_dwordx4 v[180:183], v184, s[100:101] offset:0
	global_load_dwordx4 v[188:191], v184, s[100:101] offset:528
	global_load_dwordx4 v[192:195], v184, s[100:101] offset:512
	s_add_u32 s100, s100, 0x20000
	s_addc_u32 s101, s101, 0
	global_load_dwordx4 v[196:199], v184, s[100:101] offset:16
	global_load_dwordx4 v[200:203], v184, s[100:101] offset:0
	global_load_dwordx4 v[204:207], v184, s[100:101] offset:528
	global_load_dwordx4 v[218:221], v184, s[100:101] offset:512
	s_waitcnt vmcnt(0)
	s_mov_b64 s[18:19], 0x58000
	v_pk_mul_f32 v[36:37], v[178:179], s[60:61] op_sel_hi:[1,0]
	v_pk_mul_f32 v[40:41], v[182:183], s[60:61] op_sel_hi:[1,0]
	v_pk_mul_f32 v[38:39], v[180:181], s[60:61] op_sel_hi:[1,0]
	v_pk_mul_f32 v[34:35], v[176:177], s[60:61] op_sel_hi:[1,0]
	v_pk_fma_f32 v[32:33], v[32:33], v[152:153], v[40:41]
	v_pk_fma_f32 v[30:31], v[30:31], v[154:155], v[38:39]
	v_pk_fma_f32 v[36:37], v[28:29], v[148:149], v[36:37]
	v_pk_fma_f32 v[28:29], v[26:27], v[150:151], v[34:35]
	v_lshlrev_b64 v[34:35], 1, v[42:43]
	v_cvt_pk_bf16_f32 v26, v30, v31
	v_cvt_pk_bf16_f32 v27, v32, v33
	v_cvt_pk_bf16_f32 v28, v28, v29
	v_cvt_pk_bf16_f32 v29, v36, v37
	v_lshl_add_u64 v[30:31], s[50:51], 0, v[34:35]
	global_store_dwordx4 v[30:31], v[26:29], off
	s_nop 0
	v_or_b32_e32 v34, 0x100, v34
	v_pk_mul_f32 v[28:29], v[190:191], s[60:61] op_sel_hi:[1,0]
	v_pk_mul_f32 v[32:33], v[194:195], s[60:61] op_sel_hi:[1,0]
	v_pk_mul_f32 v[30:31], v[192:193], s[60:61] op_sel_hi:[1,0]
	v_pk_mul_f32 v[26:27], v[188:189], s[60:61] op_sel_hi:[1,0]
	v_pk_fma_f32 v[24:25], v[24:25], v[144:145], v[32:33]
	v_pk_fma_f32 v[22:23], v[22:23], v[146:147], v[30:31]
	v_pk_fma_f32 v[28:29], v[20:21], v[140:141], v[28:29]
	v_pk_fma_f32 v[20:21], v[18:19], v[142:143], v[26:27]
	v_cvt_pk_bf16_f32 v18, v22, v23
	v_cvt_pk_bf16_f32 v19, v24, v25
	v_cvt_pk_bf16_f32 v20, v20, v21
	v_cvt_pk_bf16_f32 v21, v28, v29
	v_lshl_add_u64 v[22:23], s[50:51], 0, v[34:35]
	v_lshl_add_u64 v[26:27], v[156:157], 0, s[18:19]
	global_store_dwordx4 v[22:23], v[18:21], off
	v_lshl_add_u64 v[28:29], v[26:27], 2, s[0:1]
	s_mov_b64 s[0:1], -1
	v_pk_mul_f32 v[20:21], v[198:199], s[60:61] op_sel_hi:[1,0]
	v_pk_mul_f32 v[24:25], v[202:203], s[60:61] op_sel_hi:[1,0]
	v_pk_mul_f32 v[22:23], v[200:201], s[60:61] op_sel_hi:[1,0]
	v_pk_mul_f32 v[18:19], v[196:197], s[60:61] op_sel_hi:[1,0]
	v_pk_fma_f32 v[16:17], v[16:17], v[152:153], v[24:25]
	v_pk_fma_f32 v[14:15], v[14:15], v[154:155], v[22:23]
	v_pk_fma_f32 v[20:21], v[12:13], v[148:149], v[20:21]
	v_pk_fma_f32 v[12:13], v[10:11], v[150:151], v[18:19]
	v_lshlrev_b64 v[18:19], 1, v[26:27]
	v_cvt_pk_bf16_f32 v10, v14, v15
	v_cvt_pk_bf16_f32 v11, v16, v17
	v_cvt_pk_bf16_f32 v12, v12, v13
	v_cvt_pk_bf16_f32 v13, v20, v21
	v_lshl_add_u64 v[14:15], s[50:51], 0, v[18:19]
	global_store_dwordx4 v[14:15], v[10:13], off
	s_nop 0
	v_or_b32_e32 v18, 0x100, v18
	v_pk_mul_f32 v[12:13], v[206:207], s[60:61] op_sel_hi:[1,0]
	v_pk_mul_f32 v[16:17], v[220:221], s[60:61] op_sel_hi:[1,0]
	v_pk_mul_f32 v[14:15], v[218:219], s[60:61] op_sel_hi:[1,0]
	v_pk_mul_f32 v[10:11], v[204:205], s[60:61] op_sel_hi:[1,0]
	v_pk_fma_f32 v[8:9], v[8:9], v[144:145], v[16:17]
	v_pk_fma_f32 v[6:7], v[6:7], v[146:147], v[14:15]
	v_pk_fma_f32 v[12:13], v[4:5], v[140:141], v[12:13]
	v_pk_fma_f32 v[4:5], v[2:3], v[142:143], v[10:11]
	v_cvt_pk_bf16_f32 v2, v6, v7
	v_cvt_pk_bf16_f32 v3, v8, v9
	v_cvt_pk_bf16_f32 v4, v4, v5
	v_cvt_pk_bf16_f32 v5, v12, v13
	v_lshl_add_u64 v[6:7], s[50:51], 0, v[18:19]
	global_store_dwordx4 v[6:7], v[2:5], off
	s_cbranch_vccnz .LBB0_838
	s_andn2_b64 vcc, exec, s[6:7]
	s_cbranch_vccnz .LBB0_837
	s_barrier
	s_branch .LBB0_837

.LBB0_1027:
	v_lshl_or_b32 v158, s44, 8, v164
	v_ashrrev_i32_e32 v159, 31, v158
	v_lshl_add_u64 v[156:157], v[158:159], 2, s[6:7]
	global_load_dwordx4 v[140:143], v[156:157], off offset:16
	global_load_dwordx4 v[144:147], v[156:157], off
	global_load_dwordx4 v[222:225], v[156:157], off offset:528
	global_load_dwordx4 v[226:229], v[156:157], off offset:512
	v_lshl_add_u32 v160, s41, 8, v162
	v_ashrrev_i32_e32 v161, 31, v160
	v_lshl_add_u32 v184, v160, 11, v158
	v_lshlrev_b32_e32 v184, 1, v184
	s_add_u32 s100, s50, 0x0
	s_addc_u32 s101, s51, 0
	global_load_dwordx4 v[176:179], v184, s[100:101]
	global_load_dwordx4 v[180:183], v184, s[100:101] offset:256
	s_add_u32 s100, s100, 0x10000
	s_addc_u32 s101, s101, 0
	global_load_dwordx4 v[188:191], v184, s[100:101]
	global_load_dwordx4 v[192:195], v184, s[100:101] offset:256
	s_add_u32 s100, s100, 0x10000
	s_addc_u32 s101, s101, 0
	global_load_dwordx4 v[196:199], v184, s[100:101]
	global_load_dwordx4 v[200:203], v184, s[100:101] offset:256
	s_add_u32 s100, s100, 0x10000
	s_addc_u32 s101, s101, 0
	global_load_dwordx4 v[204:207], v184, s[100:101]
	global_load_dwordx4 v[218:221], v184, s[100:101] offset:256
	s_mov_b64 s[20:21], 0x40000
	s_andn2_b64 vcc, exec, s[4:5]
	s_mov_b32 s42, 0xc000
	s_waitcnt vmcnt(0)
	v_pk_add_f32 v[148:149], v[142:143], 1.0 op_sel_hi:[1,0]
	v_pk_add_f32 v[150:151], v[140:141], 1.0 op_sel_hi:[1,0]
	v_lshlrev_b64 v[156:157], 11, v[160:161]
	v_lshl_add_u64 v[156:157], v[156:157], 0, v[158:159]
	v_lshlrev_b64 v[170:171], 1, v[156:157]
	v_pk_add_f32 v[154:155], v[144:145], 1.0 op_sel_hi:[1,0]
	v_pk_add_f32 v[152:153], v[146:147], 1.0 op_sel_hi:[1,0]
	v_pk_add_f32 v[144:145], v[228:229], 1.0 op_sel_hi:[1,0]
	v_pk_add_f32 v[142:143], v[222:223], 1.0 op_sel_hi:[1,0]
	v_lshl_add_u64 v[166:167], s[50:51], 0, v[170:171]
	v_pk_add_f32 v[146:147], v[226:227], 1.0 op_sel_hi:[1,0]
	v_pk_add_f32 v[140:141], v[224:225], 1.0 op_sel_hi:[1,0]
	v_or_b32_e32 v170, 0x100, v170
	v_lshlrev_b32_e32 v172, 16, v176
	v_and_b32_e32 v173, 0xffff0000, v176
	v_lshlrev_b32_e32 v166, 16, v177
	v_and_b32_e32 v167, 0xffff0000, v177
	v_lshlrev_b32_e32 v174, 16, v178
	v_and_b32_e32 v175, 0xffff0000, v178
	v_pk_mul_f32 v[166:167], v[166:167], s[60:61] op_sel_hi:[1,0]
	v_lshlrev_b32_e32 v168, 16, v179
	v_and_b32_e32 v169, 0xffff0000, v179
	v_pk_mul_f32 v[172:173], v[172:173], s[60:61] op_sel_hi:[1,0]
	v_pk_fma_f32 v[128:129], v[128:129], v[152:153], v[166:167]
	v_pk_mul_f32 v[166:167], v[174:175], s[60:61] op_sel_hi:[1,0]
	v_pk_fma_f32 v[126:127], v[126:127], v[154:155], v[172:173]
	v_pk_mul_f32 v[168:169], v[168:169], s[60:61] op_sel_hi:[1,0]
	v_pk_fma_f32 v[122:123], v[122:123], v[150:151], v[166:167]
	v_lshl_add_u64 v[166:167], v[156:157], 2, s[36:37]
	v_pk_fma_f32 v[124:125], v[124:125], v[148:149], v[168:169]
	global_store_dwordx4 v[166:167], v[126:129], off
	global_store_dwordx4 v[166:167], v[122:125], off offset:16
	s_nop 1
	v_lshl_add_u64 v[122:123], s[50:51], 0, v[170:171]
	v_lshlrev_b32_e32 v126, 16, v180
	v_and_b32_e32 v127, 0xffff0000, v180
	v_lshlrev_b32_e32 v122, 16, v181
	v_and_b32_e32 v123, 0xffff0000, v181
	v_lshlrev_b32_e32 v128, 16, v182
	v_and_b32_e32 v129, 0xffff0000, v182
	v_pk_mul_f32 v[122:123], v[122:123], s[60:61] op_sel_hi:[1,0]
	v_lshlrev_b32_e32 v124, 16, v183
	v_and_b32_e32 v125, 0xffff0000, v183
	v_pk_mul_f32 v[126:127], v[126:127], s[60:61] op_sel_hi:[1,0]
	v_pk_fma_f32 v[120:121], v[120:121], v[144:145], v[122:123]
	v_pk_mul_f32 v[122:123], v[128:129], s[60:61] op_sel_hi:[1,0]
	v_pk_fma_f32 v[118:119], v[118:119], v[146:147], v[126:127]
	v_pk_mul_f32 v[124:125], v[124:125], s[60:61] op_sel_hi:[1,0]
	v_pk_fma_f32 v[114:115], v[114:115], v[142:143], v[122:123]
	v_pk_fma_f32 v[116:117], v[116:117], v[140:141], v[124:125]
	global_store_dwordx4 v[166:167], v[118:121], off offset:512
	global_store_dwordx4 v[166:167], v[114:117], off offset:528
	s_nop 1
	v_or_b32_e32 v114, 16, v160
	v_ashrrev_i32_e32 v115, 31, v114
	v_lshlrev_b64 v[114:115], 11, v[114:115]
	v_lshl_add_u64 v[118:119], v[114:115], 0, v[158:159]
	v_lshlrev_b64 v[120:121], 1, v[118:119]
	v_lshl_add_u64 v[114:115], s[50:51], 0, v[120:121]
	v_or_b32_e32 v120, 0x100, v120
	v_lshlrev_b32_e32 v122, 16, v188
	v_and_b32_e32 v123, 0xffff0000, v188
	v_lshlrev_b32_e32 v114, 16, v189
	v_and_b32_e32 v115, 0xffff0000, v189
	v_lshlrev_b32_e32 v124, 16, v190
	v_and_b32_e32 v125, 0xffff0000, v190
	v_pk_mul_f32 v[114:115], v[114:115], s[60:61] op_sel_hi:[1,0]
	v_lshlrev_b32_e32 v116, 16, v191
	v_and_b32_e32 v117, 0xffff0000, v191
	v_pk_mul_f32 v[122:123], v[122:123], s[60:61] op_sel_hi:[1,0]
	v_pk_fma_f32 v[112:113], v[112:113], v[152:153], v[114:115]
	v_pk_mul_f32 v[114:115], v[124:125], s[60:61] op_sel_hi:[1,0]
	v_pk_fma_f32 v[110:111], v[110:111], v[154:155], v[122:123]
	v_pk_mul_f32 v[116:117], v[116:117], s[60:61] op_sel_hi:[1,0]
	v_pk_fma_f32 v[106:107], v[106:107], v[150:151], v[114:115]
	v_lshl_add_u64 v[114:115], v[118:119], 2, s[36:37]
	v_pk_fma_f32 v[108:109], v[108:109], v[148:149], v[116:117]
	global_store_dwordx4 v[114:115], v[110:113], off
	global_store_dwordx4 v[114:115], v[106:109], off offset:16
	s_nop 1
	v_lshl_add_u64 v[106:107], s[50:51], 0, v[120:121]
	v_lshlrev_b32_e32 v110, 16, v192
	v_and_b32_e32 v111, 0xffff0000, v192
	v_lshlrev_b32_e32 v106, 16, v193
	v_and_b32_e32 v107, 0xffff0000, v193
	v_lshlrev_b32_e32 v112, 16, v194
	v_and_b32_e32 v113, 0xffff0000, v194
	v_pk_mul_f32 v[106:107], v[106:107], s[60:61] op_sel_hi:[1,0]
	v_lshlrev_b32_e32 v108, 16, v195
	v_and_b32_e32 v109, 0xffff0000, v195
	v_pk_mul_f32 v[110:111], v[110:111], s[60:61] op_sel_hi:[1,0]
	v_pk_fma_f32 v[104:105], v[104:105], v[144:145], v[106:107]
	v_pk_mul_f32 v[106:107], v[112:113], s[60:61] op_sel_hi:[1,0]
	v_pk_fma_f32 v[102:103], v[102:103], v[146:147], v[110:111]
	v_pk_mul_f32 v[108:109], v[108:109], s[60:61] op_sel_hi:[1,0]
	v_pk_fma_f32 v[98:99], v[98:99], v[142:143], v[106:107]
	v_pk_fma_f32 v[100:101], v[100:101], v[140:141], v[108:109]
	global_store_dwordx4 v[114:115], v[102:105], off offset:512
	global_store_dwordx4 v[114:115], v[98:101], off offset:528
	s_nop 1
	v_or_b32_e32 v98, 32, v160
	v_ashrrev_i32_e32 v99, 31, v98
	v_lshlrev_b64 v[98:99], 11, v[98:99]
	v_lshl_add_u64 v[102:103], v[98:99], 0, v[158:159]
	v_lshlrev_b64 v[104:105], 1, v[102:103]
	v_lshl_add_u64 v[98:99], s[50:51], 0, v[104:105]
	v_or_b32_e32 v104, 0x100, v104
	v_lshlrev_b32_e32 v106, 16, v196
	v_and_b32_e32 v107, 0xffff0000, v196
	v_lshlrev_b32_e32 v98, 16, v197
	v_and_b32_e32 v99, 0xffff0000, v197
	v_lshlrev_b32_e32 v108, 16, v198
	v_and_b32_e32 v109, 0xffff0000, v198
	v_pk_mul_f32 v[98:99], v[98:99], s[60:61] op_sel_hi:[1,0]
	v_lshlrev_b32_e32 v100, 16, v199
	v_and_b32_e32 v101, 0xffff0000, v199
	v_pk_mul_f32 v[106:107], v[106:107], s[60:61] op_sel_hi:[1,0]
	v_pk_fma_f32 v[96:97], v[96:97], v[152:153], v[98:99]
	v_pk_mul_f32 v[98:99], v[108:109], s[60:61] op_sel_hi:[1,0]
	v_pk_fma_f32 v[94:95], v[94:95], v[154:155], v[106:107]
	v_pk_mul_f32 v[100:101], v[100:101], s[60:61] op_sel_hi:[1,0]
	v_pk_fma_f32 v[90:91], v[90:91], v[150:151], v[98:99]
	v_lshl_add_u64 v[98:99], v[102:103], 2, s[36:37]
	v_pk_fma_f32 v[92:93], v[92:93], v[148:149], v[100:101]
	global_store_dwordx4 v[98:99], v[94:97], off
	global_store_dwordx4 v[98:99], v[90:93], off offset:16
	s_nop 1
	v_lshl_add_u64 v[90:91], s[50:51], 0, v[104:105]
	v_lshlrev_b32_e32 v94, 16, v200
	v_and_b32_e32 v95, 0xffff0000, v200
	v_lshlrev_b32_e32 v90, 16, v201
	v_and_b32_e32 v91, 0xffff0000, v201
	v_lshlrev_b32_e32 v96, 16, v202
	v_and_b32_e32 v97, 0xffff0000, v202
	v_pk_mul_f32 v[90:91], v[90:91], s[60:61] op_sel_hi:[1,0]
	v_lshlrev_b32_e32 v92, 16, v203
	v_and_b32_e32 v93, 0xffff0000, v203
	v_pk_mul_f32 v[94:95], v[94:95], s[60:61] op_sel_hi:[1,0]
	v_pk_fma_f32 v[88:89], v[88:89], v[144:145], v[90:91]
	v_pk_mul_f32 v[90:91], v[96:97], s[60:61] op_sel_hi:[1,0]
	v_pk_fma_f32 v[86:87], v[86:87], v[146:147], v[94:95]
	v_pk_mul_f32 v[92:93], v[92:93], s[60:61] op_sel_hi:[1,0]
	v_pk_fma_f32 v[82:83], v[82:83], v[142:143], v[90:91]
	v_pk_fma_f32 v[84:85], v[84:85], v[140:141], v[92:93]
	global_store_dwordx4 v[98:99], v[86:89], off offset:512
	global_store_dwordx4 v[98:99], v[82:85], off offset:528
	s_nop 1
	v_or_b32_e32 v82, 48, v160
	v_ashrrev_i32_e32 v83, 31, v82
	v_lshlrev_b64 v[82:83], 11, v[82:83]
	v_lshl_add_u64 v[86:87], v[82:83], 0, v[158:159]
	v_lshlrev_b64 v[88:89], 1, v[86:87]
	v_lshl_add_u64 v[82:83], s[50:51], 0, v[88:89]
	v_or_b32_e32 v88, 0x100, v88
	v_lshlrev_b32_e32 v90, 16, v204
	v_and_b32_e32 v91, 0xffff0000, v204
	v_lshlrev_b32_e32 v82, 16, v205
	v_and_b32_e32 v83, 0xffff0000, v205
	v_lshlrev_b32_e32 v92, 16, v206
	v_and_b32_e32 v93, 0xffff0000, v206
	v_pk_mul_f32 v[82:83], v[82:83], s[60:61] op_sel_hi:[1,0]
	v_lshlrev_b32_e32 v84, 16, v207
	v_and_b32_e32 v85, 0xffff0000, v207
	v_pk_mul_f32 v[90:91], v[90:91], s[60:61] op_sel_hi:[1,0]
	v_pk_fma_f32 v[80:81], v[80:81], v[152:153], v[82:83]
	v_pk_mul_f32 v[82:83], v[92:93], s[60:61] op_sel_hi:[1,0]
	v_pk_fma_f32 v[78:79], v[78:79], v[154:155], v[90:91]
	v_pk_mul_f32 v[84:85], v[84:85], s[60:61] op_sel_hi:[1,0]
	v_pk_fma_f32 v[74:75], v[74:75], v[150:151], v[82:83]
	v_lshl_add_u64 v[82:83], v[86:87], 2, s[36:37]
	v_pk_fma_f32 v[76:77], v[76:77], v[148:149], v[84:85]
	global_store_dwordx4 v[82:83], v[78:81], off
	global_store_dwordx4 v[82:83], v[74:77], off offset:16
	s_nop 1
	v_lshl_add_u64 v[74:75], s[50:51], 0, v[88:89]
	v_lshlrev_b32_e32 v78, 16, v218
	v_and_b32_e32 v79, 0xffff0000, v218
	v_lshlrev_b32_e32 v74, 16, v219
	v_and_b32_e32 v75, 0xffff0000, v219
	v_lshlrev_b32_e32 v80, 16, v220
	v_and_b32_e32 v81, 0xffff0000, v220
	v_lshlrev_b32_e32 v76, 16, v221
	v_and_b32_e32 v77, 0xffff0000, v221
	v_pk_mul_f32 v[78:79], v[78:79], s[60:61] op_sel_hi:[1,0]
	v_pk_mul_f32 v[74:75], v[74:75], s[60:61] op_sel_hi:[1,0]
	v_pk_fma_f32 v[70:71], v[70:71], v[146:147], v[78:79]
	v_pk_fma_f32 v[72:73], v[72:73], v[144:145], v[74:75]
	v_pk_mul_f32 v[74:75], v[80:81], s[60:61] op_sel_hi:[1,0]
	v_pk_mul_f32 v[76:77], v[76:77], s[60:61] op_sel_hi:[1,0]
	v_pk_fma_f32 v[66:67], v[66:67], v[142:143], v[74:75]
	v_pk_fma_f32 v[68:69], v[68:69], v[140:141], v[76:77]
	global_store_dwordx4 v[82:83], v[70:73], off offset:512
	global_store_dwordx4 v[82:83], v[66:69], off offset:528
	s_nop 0
	v_lshl_add_u64 v[70:71], v[156:157], 0, s[20:21]
	v_lshlrev_b64 v[72:73], 1, v[70:71]
	v_lshl_add_u64 v[66:67], s[50:51], 0, v[72:73]
	v_lshlrev_b32_e32 v184, 1, v156
	s_add_u32 s100, s50, 0x80000
	s_addc_u32 s101, s51, 0
	global_load_dwordx4 v[176:179], v184, s[100:101]
	global_load_dwordx4 v[180:183], v184, s[100:101] offset:256
	s_add_u32 s100, s100, 0x10000
	s_addc_u32 s101, s101, 0
	global_load_dwordx4 v[188:191], v184, s[100:101]
	global_load_dwordx4 v[192:195], v184, s[100:101] offset:256
	s_add_u32 s100, s100, 0x10000
	s_addc_u32 s101, s101, 0
	global_load_dwordx4 v[196:199], v184, s[100:101]
	global_load_dwordx4 v[200:203], v184, s[100:101] offset:256
	s_add_u32 s100, s100, 0x10000
	s_addc_u32 s101, s101, 0
	global_load_dwordx4 v[204:207], v184, s[100:101]
	global_load_dwordx4 v[218:221], v184, s[100:101] offset:256
	s_waitcnt vmcnt(0)
	v_or_b32_e32 v72, 0x100, v72
	s_mov_b64 s[20:21], 0x48000
	v_lshlrev_b32_e32 v74, 16, v176
	v_and_b32_e32 v75, 0xffff0000, v176
	v_lshlrev_b32_e32 v66, 16, v177
	v_and_b32_e32 v67, 0xffff0000, v177
	v_lshlrev_b32_e32 v76, 16, v178
	v_and_b32_e32 v77, 0xffff0000, v178
	v_pk_mul_f32 v[66:67], v[66:67], s[60:61] op_sel_hi:[1,0]
	v_lshlrev_b32_e32 v68, 16, v179
	v_and_b32_e32 v69, 0xffff0000, v179
	v_pk_mul_f32 v[74:75], v[74:75], s[60:61] op_sel_hi:[1,0]
	v_pk_fma_f32 v[64:65], v[64:65], v[152:153], v[66:67]
	v_pk_mul_f32 v[66:67], v[76:77], s[60:61] op_sel_hi:[1,0]
	v_pk_fma_f32 v[62:63], v[62:63], v[154:155], v[74:75]
	v_pk_mul_f32 v[68:69], v[68:69], s[60:61] op_sel_hi:[1,0]
	v_pk_fma_f32 v[58:59], v[58:59], v[150:151], v[66:67]
	v_lshl_add_u64 v[66:67], v[70:71], 2, s[36:37]
	v_pk_fma_f32 v[60:61], v[60:61], v[148:149], v[68:69]
	global_store_dwordx4 v[66:67], v[62:65], off
	global_store_dwordx4 v[66:67], v[58:61], off offset:16
	s_nop 1
	v_lshl_add_u64 v[58:59], s[50:51], 0, v[72:73]
	v_lshlrev_b32_e32 v62, 16, v180
	v_and_b32_e32 v63, 0xffff0000, v180
	v_lshlrev_b32_e32 v58, 16, v181
	v_and_b32_e32 v59, 0xffff0000, v181
	v_lshlrev_b32_e32 v64, 16, v182
	v_and_b32_e32 v65, 0xffff0000, v182
	v_lshlrev_b32_e32 v60, 16, v183
	v_and_b32_e32 v61, 0xffff0000, v183
	v_pk_mul_f32 v[62:63], v[62:63], s[60:61] op_sel_hi:[1,0]
	v_pk_mul_f32 v[58:59], v[58:59], s[60:61] op_sel_hi:[1,0]
	v_pk_fma_f32 v[54:55], v[54:55], v[146:147], v[62:63]
	v_pk_fma_f32 v[56:57], v[56:57], v[144:145], v[58:59]
	v_pk_mul_f32 v[58:59], v[64:65], s[60:61] op_sel_hi:[1,0]
	v_pk_mul_f32 v[60:61], v[60:61], s[60:61] op_sel_hi:[1,0]
	v_pk_fma_f32 v[50:51], v[50:51], v[142:143], v[58:59]
	v_pk_fma_f32 v[52:53], v[52:53], v[140:141], v[60:61]
	global_store_dwordx4 v[66:67], v[54:57], off offset:512
	global_store_dwordx4 v[66:67], v[50:53], off offset:528
	s_nop 0
	v_lshl_add_u64 v[54:55], v[156:157], 0, s[20:21]
	v_lshlrev_b64 v[56:57], 1, v[54:55]
	v_lshl_add_u64 v[50:51], s[50:51], 0, v[56:57]
	v_or_b32_e32 v56, 0x100, v56
	s_mov_b64 s[20:21], 0x50000
	v_lshlrev_b32_e32 v58, 16, v188
	v_and_b32_e32 v59, 0xffff0000, v188
	v_lshlrev_b32_e32 v50, 16, v189
	v_and_b32_e32 v51, 0xffff0000, v189
	v_lshlrev_b32_e32 v60, 16, v190
	v_and_b32_e32 v61, 0xffff0000, v190
	v_pk_mul_f32 v[50:51], v[50:51], s[60:61] op_sel_hi:[1,0]
	v_lshlrev_b32_e32 v52, 16, v191
	v_and_b32_e32 v53, 0xffff0000, v191
	v_pk_mul_f32 v[58:59], v[58:59], s[60:61] op_sel_hi:[1,0]
	v_pk_fma_f32 v[48:49], v[48:49], v[152:153], v[50:51]
	v_pk_mul_f32 v[50:51], v[60:61], s[60:61] op_sel_hi:[1,0]
	v_pk_fma_f32 v[46:47], v[46:47], v[154:155], v[58:59]
	v_pk_mul_f32 v[52:53], v[52:53], s[60:61] op_sel_hi:[1,0]
	v_pk_fma_f32 v[42:43], v[42:43], v[150:151], v[50:51]
	v_lshl_add_u64 v[50:51], v[54:55], 2, s[36:37]
	v_pk_fma_f32 v[44:45], v[44:45], v[148:149], v[52:53]
	global_store_dwordx4 v[50:51], v[46:49], off
	global_store_dwordx4 v[50:51], v[42:45], off offset:16
	s_nop 1
	v_lshl_add_u64 v[42:43], s[50:51], 0, v[56:57]
	v_lshlrev_b32_e32 v46, 16, v192
	v_and_b32_e32 v47, 0xffff0000, v192
	v_lshlrev_b32_e32 v42, 16, v193
	v_and_b32_e32 v43, 0xffff0000, v193
	v_lshlrev_b32_e32 v48, 16, v194
	v_and_b32_e32 v49, 0xffff0000, v194
	v_lshlrev_b32_e32 v44, 16, v195
	v_and_b32_e32 v45, 0xffff0000, v195
	v_pk_mul_f32 v[46:47], v[46:47], s[60:61] op_sel_hi:[1,0]
	v_pk_mul_f32 v[42:43], v[42:43], s[60:61] op_sel_hi:[1,0]
	v_pk_fma_f32 v[38:39], v[38:39], v[146:147], v[46:47]
	v_pk_fma_f32 v[40:41], v[40:41], v[144:145], v[42:43]
	v_pk_mul_f32 v[42:43], v[48:49], s[60:61] op_sel_hi:[1,0]
	v_pk_mul_f32 v[44:45], v[44:45], s[60:61] op_sel_hi:[1,0]
	v_pk_fma_f32 v[34:35], v[34:35], v[142:143], v[42:43]
	v_pk_fma_f32 v[36:37], v[36:37], v[140:141], v[44:45]
	global_store_dwordx4 v[50:51], v[38:41], off offset:512
	global_store_dwordx4 v[50:51], v[34:37], off offset:528
	s_nop 0
	v_lshl_add_u64 v[38:39], v[156:157], 0, s[20:21]
	v_lshlrev_b64 v[40:41], 1, v[38:39]
	v_lshl_add_u64 v[34:35], s[50:51], 0, v[40:41]
	v_or_b32_e32 v40, 0x100, v40
	s_mov_b64 s[20:21], 0x58000
	v_lshlrev_b32_e32 v42, 16, v196
	v_and_b32_e32 v43, 0xffff0000, v196
	v_lshlrev_b32_e32 v34, 16, v197
	v_and_b32_e32 v35, 0xffff0000, v197
	v_lshlrev_b32_e32 v44, 16, v198
	v_and_b32_e32 v45, 0xffff0000, v198
	v_pk_mul_f32 v[34:35], v[34:35], s[60:61] op_sel_hi:[1,0]
	v_lshlrev_b32_e32 v36, 16, v199
	v_and_b32_e32 v37, 0xffff0000, v199
	v_pk_mul_f32 v[42:43], v[42:43], s[60:61] op_sel_hi:[1,0]
	v_pk_fma_f32 v[32:33], v[32:33], v[152:153], v[34:35]
	v_pk_mul_f32 v[34:35], v[44:45], s[60:61] op_sel_hi:[1,0]
	v_pk_fma_f32 v[30:31], v[30:31], v[154:155], v[42:43]
	v_pk_mul_f32 v[36:37], v[36:37], s[60:61] op_sel_hi:[1,0]
	v_pk_fma_f32 v[26:27], v[26:27], v[150:151], v[34:35]
	v_lshl_add_u64 v[34:35], v[38:39], 2, s[36:37]
	v_pk_fma_f32 v[28:29], v[28:29], v[148:149], v[36:37]
	global_store_dwordx4 v[34:35], v[30:33], off
	global_store_dwordx4 v[34:35], v[26:29], off offset:16
	s_nop 1
	v_lshl_add_u64 v[26:27], s[50:51], 0, v[40:41]
	v_lshlrev_b32_e32 v30, 16, v200
	v_and_b32_e32 v31, 0xffff0000, v200
	v_lshlrev_b32_e32 v26, 16, v201
	v_and_b32_e32 v27, 0xffff0000, v201
	v_lshlrev_b32_e32 v32, 16, v202
	v_and_b32_e32 v33, 0xffff0000, v202
	v_lshlrev_b32_e32 v28, 16, v203
	v_and_b32_e32 v29, 0xffff0000, v203
	v_pk_mul_f32 v[30:31], v[30:31], s[60:61] op_sel_hi:[1,0]
	v_pk_mul_f32 v[26:27], v[26:27], s[60:61] op_sel_hi:[1,0]
	v_pk_fma_f32 v[22:23], v[22:23], v[146:147], v[30:31]
	v_pk_fma_f32 v[24:25], v[24:25], v[144:145], v[26:27]
	v_pk_mul_f32 v[26:27], v[32:33], s[60:61] op_sel_hi:[1,0]
	v_pk_mul_f32 v[28:29], v[28:29], s[60:61] op_sel_hi:[1,0]
	v_pk_fma_f32 v[18:19], v[18:19], v[142:143], v[26:27]
	v_pk_fma_f32 v[20:21], v[20:21], v[140:141], v[28:29]
	global_store_dwordx4 v[34:35], v[22:25], off offset:512
	global_store_dwordx4 v[34:35], v[18:21], off offset:528
	s_nop 0
	v_lshl_add_u64 v[22:23], v[156:157], 0, s[20:21]
	v_lshlrev_b64 v[24:25], 1, v[22:23]
	v_lshl_add_u64 v[18:19], s[50:51], 0, v[24:25]
	v_or_b32_e32 v24, 0x100, v24
	s_mov_b64 s[20:21], -1
	v_lshlrev_b32_e32 v26, 16, v204
	v_and_b32_e32 v27, 0xffff0000, v204
	v_lshlrev_b32_e32 v18, 16, v205
	v_and_b32_e32 v19, 0xffff0000, v205
	v_lshlrev_b32_e32 v28, 16, v206
	v_and_b32_e32 v29, 0xffff0000, v206
	v_pk_mul_f32 v[18:19], v[18:19], s[60:61] op_sel_hi:[1,0]
	v_lshlrev_b32_e32 v20, 16, v207
	v_and_b32_e32 v21, 0xffff0000, v207
	v_pk_mul_f32 v[26:27], v[26:27], s[60:61] op_sel_hi:[1,0]
	v_pk_fma_f32 v[16:17], v[16:17], v[152:153], v[18:19]
	v_pk_mul_f32 v[18:19], v[28:29], s[60:61] op_sel_hi:[1,0]
	v_pk_fma_f32 v[14:15], v[14:15], v[154:155], v[26:27]
	v_pk_mul_f32 v[20:21], v[20:21], s[60:61] op_sel_hi:[1,0]
	v_pk_fma_f32 v[10:11], v[10:11], v[150:151], v[18:19]
	v_lshl_add_u64 v[18:19], v[22:23], 2, s[36:37]
	v_pk_fma_f32 v[12:13], v[12:13], v[148:149], v[20:21]
	global_store_dwordx4 v[18:19], v[14:17], off
	global_store_dwordx4 v[18:19], v[10:13], off offset:16
	s_nop 1
	v_lshl_add_u64 v[10:11], s[50:51], 0, v[24:25]
	v_lshlrev_b32_e32 v14, 16, v218
	v_and_b32_e32 v15, 0xffff0000, v218
	v_lshlrev_b32_e32 v10, 16, v219
	v_and_b32_e32 v11, 0xffff0000, v219
	v_lshlrev_b32_e32 v16, 16, v220
	v_and_b32_e32 v17, 0xffff0000, v220
	v_lshlrev_b32_e32 v12, 16, v221
	v_and_b32_e32 v13, 0xffff0000, v221
	v_pk_mul_f32 v[14:15], v[14:15], s[60:61] op_sel_hi:[1,0]
	v_pk_mul_f32 v[10:11], v[10:11], s[60:61] op_sel_hi:[1,0]
	v_pk_fma_f32 v[6:7], v[6:7], v[146:147], v[14:15]
	v_pk_fma_f32 v[8:9], v[8:9], v[144:145], v[10:11]
	v_pk_mul_f32 v[10:11], v[16:17], s[60:61] op_sel_hi:[1,0]
	v_pk_mul_f32 v[12:13], v[12:13], s[60:61] op_sel_hi:[1,0]
	v_pk_fma_f32 v[2:3], v[2:3], v[142:143], v[10:11]
	v_pk_fma_f32 v[4:5], v[4:5], v[140:141], v[12:13]
	global_store_dwordx4 v[18:19], v[6:9], off offset:512
	global_store_dwordx4 v[18:19], v[2:5], off offset:528
	s_cbranch_vccnz .LBB0_1016
	s_andn2_b64 vcc, exec, s[8:9]
	s_cbranch_vccnz .LBB0_1015
	s_barrier
	s_branch .LBB0_1015

.LBB0_1049:
	v_lshl_or_b32 v160, s40, 8, v164
	v_ashrrev_i32_e32 v161, 31, v160
	v_lshl_add_u64 v[166:167], v[160:161], 2, s[6:7]
	global_load_dwordx4 v[140:143], v[166:167], off offset:16
	global_load_dwordx4 v[144:147], v[166:167], off
	global_load_dwordx4 v[222:225], v[166:167], off offset:528
	global_load_dwordx4 v[226:229], v[166:167], off offset:512
	v_lshlrev_b64 v[160:161], 1, v[160:161]
	v_lshl_add_u32 v185, s35, 8, v162
	v_lshl_add_u32 v184, v185, 12, v160
	s_add_u32 s100, s50, 0x0
	s_addc_u32 s101, s51, 0
	global_load_dwordx4 v[176:179], v184, s[100:101]
	global_load_dwordx4 v[180:183], v184, s[100:101] offset:256
	s_add_u32 s100, s100, 0x10000
	s_addc_u32 s101, s101, 0
	global_load_dwordx4 v[188:191], v184, s[100:101]
	global_load_dwordx4 v[192:195], v184, s[100:101] offset:256
	s_add_u32 s100, s100, 0x10000
	s_addc_u32 s101, s101, 0
	global_load_dwordx4 v[196:199], v184, s[100:101]
	global_load_dwordx4 v[200:203], v184, s[100:101] offset:256
	s_add_u32 s100, s100, 0x10000
	s_addc_u32 s101, s101, 0
	global_load_dwordx4 v[204:207], v184, s[100:101]
	global_load_dwordx4 v[218:221], v184, s[100:101] offset:256
	s_mov_b32 s3, 0x80000
	s_mov_b64 s[18:19], 0x80000
	s_mov_b32 s42, 0xc000
	s_waitcnt vmcnt(0)
	v_pk_add_f32 v[148:149], v[142:143], 1.0 op_sel_hi:[1,0]
	v_pk_add_f32 v[150:151], v[140:141], 1.0 op_sel_hi:[1,0]
	v_pk_add_f32 v[152:153], v[146:147], 1.0 op_sel_hi:[1,0]
	v_pk_add_f32 v[154:155], v[144:145], 1.0 op_sel_hi:[1,0]
	v_pk_add_f32 v[146:147], v[226:227], 1.0 op_sel_hi:[1,0]
	v_pk_add_f32 v[140:141], v[224:225], 1.0 op_sel_hi:[1,0]
	v_lshl_add_u32 v158, s35, 8, v162
	v_ashrrev_i32_e32 v159, 31, v158
	v_pk_add_f32 v[144:145], v[228:229], 1.0 op_sel_hi:[1,0]
	v_pk_add_f32 v[142:143], v[222:223], 1.0 op_sel_hi:[1,0]
	v_lshlrev_b64 v[156:157], 12, v[158:159]
	v_lshl_add_u64 v[156:157], s[50:51], 0, v[156:157]
	v_lshl_add_u64 v[156:157], v[156:157], 0, v[160:161]
	v_lshlrev_b32_e32 v170, 16, v176
	v_and_b32_e32 v171, 0xffff0000, v176
	v_lshlrev_b32_e32 v166, 16, v177
	v_and_b32_e32 v167, 0xffff0000, v177
	v_lshlrev_b32_e32 v172, 16, v178
	v_and_b32_e32 v173, 0xffff0000, v178
	v_lshlrev_b32_e32 v168, 16, v179
	v_and_b32_e32 v169, 0xffff0000, v179
	v_pk_mul_f32 v[166:167], v[166:167], s[60:61] op_sel_hi:[1,0]
	v_pk_mul_f32 v[170:171], v[170:171], s[60:61] op_sel_hi:[1,0]
	v_pk_fma_f32 v[128:129], v[128:129], v[152:153], v[166:167]
	v_pk_mul_f32 v[166:167], v[172:173], s[60:61] op_sel_hi:[1,0]
	v_pk_mul_f32 v[168:169], v[168:169], s[60:61] op_sel_hi:[1,0]
	v_pk_fma_f32 v[126:127], v[126:127], v[154:155], v[170:171]
	v_pk_fma_f32 v[168:169], v[124:125], v[148:149], v[168:169]
	v_pk_fma_f32 v[124:125], v[122:123], v[150:151], v[166:167]
	v_cvt_pk_bf16_f32 v122, v126, v127
	v_cvt_pk_bf16_f32 v123, v128, v129
	v_cvt_pk_bf16_f32 v124, v124, v125
	v_cvt_pk_bf16_f32 v125, v168, v169
	global_store_dwordx4 v[156:157], v[122:125], off
	v_lshlrev_b32_e32 v126, 16, v180
	v_and_b32_e32 v127, 0xffff0000, v180
	v_lshlrev_b32_e32 v122, 16, v181
	v_and_b32_e32 v123, 0xffff0000, v181
	v_lshlrev_b32_e32 v128, 16, v182
	v_and_b32_e32 v129, 0xffff0000, v182
	v_lshlrev_b32_e32 v124, 16, v183
	v_and_b32_e32 v125, 0xffff0000, v183
	v_pk_mul_f32 v[122:123], v[122:123], s[60:61] op_sel_hi:[1,0]
	v_pk_mul_f32 v[126:127], v[126:127], s[60:61] op_sel_hi:[1,0]
	v_pk_fma_f32 v[120:121], v[120:121], v[144:145], v[122:123]
	v_pk_mul_f32 v[122:123], v[128:129], s[60:61] op_sel_hi:[1,0]
	v_pk_mul_f32 v[124:125], v[124:125], s[60:61] op_sel_hi:[1,0]
	v_pk_fma_f32 v[118:119], v[118:119], v[146:147], v[126:127]
	v_pk_fma_f32 v[124:125], v[116:117], v[140:141], v[124:125]
	v_pk_fma_f32 v[116:117], v[114:115], v[142:143], v[122:123]
	v_cvt_pk_bf16_f32 v114, v118, v119
	v_cvt_pk_bf16_f32 v115, v120, v121
	v_cvt_pk_bf16_f32 v116, v116, v117
	v_cvt_pk_bf16_f32 v117, v124, v125
	global_store_dwordx4 v[156:157], v[114:117], off offset:256
	s_nop 1
	v_or_b32_e32 v114, 16, v158
	v_ashrrev_i32_e32 v115, 31, v114
	v_lshlrev_b64 v[114:115], 12, v[114:115]
	v_lshl_add_u64 v[114:115], s[50:51], 0, v[114:115]
	v_lshl_add_u64 v[118:119], v[114:115], 0, v[160:161]
	v_lshlrev_b32_e32 v120, 16, v188
	v_and_b32_e32 v121, 0xffff0000, v188
	v_lshlrev_b32_e32 v114, 16, v189
	v_and_b32_e32 v115, 0xffff0000, v189
	v_lshlrev_b32_e32 v122, 16, v190
	v_and_b32_e32 v123, 0xffff0000, v190
	v_lshlrev_b32_e32 v116, 16, v191
	v_and_b32_e32 v117, 0xffff0000, v191
	v_pk_mul_f32 v[114:115], v[114:115], s[60:61] op_sel_hi:[1,0]
	v_pk_mul_f32 v[120:121], v[120:121], s[60:61] op_sel_hi:[1,0]
	v_pk_fma_f32 v[112:113], v[112:113], v[152:153], v[114:115]
	v_pk_mul_f32 v[114:115], v[122:123], s[60:61] op_sel_hi:[1,0]
	v_pk_mul_f32 v[116:117], v[116:117], s[60:61] op_sel_hi:[1,0]
	v_pk_fma_f32 v[110:111], v[110:111], v[154:155], v[120:121]
	v_pk_fma_f32 v[116:117], v[108:109], v[148:149], v[116:117]
	v_pk_fma_f32 v[108:109], v[106:107], v[150:151], v[114:115]
	v_cvt_pk_bf16_f32 v106, v110, v111
	v_cvt_pk_bf16_f32 v107, v112, v113
	v_cvt_pk_bf16_f32 v108, v108, v109
	v_cvt_pk_bf16_f32 v109, v116, v117
	global_store_dwordx4 v[118:119], v[106:109], off
	v_lshlrev_b32_e32 v110, 16, v192
	v_and_b32_e32 v111, 0xffff0000, v192
	v_lshlrev_b32_e32 v106, 16, v193
	v_and_b32_e32 v107, 0xffff0000, v193
	v_lshlrev_b32_e32 v112, 16, v194
	v_and_b32_e32 v113, 0xffff0000, v194
	v_lshlrev_b32_e32 v108, 16, v195
	v_and_b32_e32 v109, 0xffff0000, v195
	v_pk_mul_f32 v[106:107], v[106:107], s[60:61] op_sel_hi:[1,0]
	v_pk_mul_f32 v[110:111], v[110:111], s[60:61] op_sel_hi:[1,0]
	v_pk_fma_f32 v[104:105], v[104:105], v[144:145], v[106:107]
	v_pk_mul_f32 v[106:107], v[112:113], s[60:61] op_sel_hi:[1,0]
	v_pk_mul_f32 v[108:109], v[108:109], s[60:61] op_sel_hi:[1,0]
	v_pk_fma_f32 v[102:103], v[102:103], v[146:147], v[110:111]
	v_pk_fma_f32 v[108:109], v[100:101], v[140:141], v[108:109]
	v_pk_fma_f32 v[100:101], v[98:99], v[142:143], v[106:107]
	v_cvt_pk_bf16_f32 v98, v102, v103
	v_cvt_pk_bf16_f32 v99, v104, v105
	v_cvt_pk_bf16_f32 v100, v100, v101
	v_cvt_pk_bf16_f32 v101, v108, v109
	global_store_dwordx4 v[118:119], v[98:101], off offset:256
	s_nop 1
	v_or_b32_e32 v98, 32, v158
	v_ashrrev_i32_e32 v99, 31, v98
	v_lshlrev_b64 v[98:99], 12, v[98:99]
	v_lshl_add_u64 v[98:99], s[50:51], 0, v[98:99]
	v_lshl_add_u64 v[102:103], v[98:99], 0, v[160:161]
	v_lshlrev_b32_e32 v104, 16, v196
	v_and_b32_e32 v105, 0xffff0000, v196
	v_lshlrev_b32_e32 v98, 16, v197
	v_and_b32_e32 v99, 0xffff0000, v197
	v_lshlrev_b32_e32 v106, 16, v198
	v_and_b32_e32 v107, 0xffff0000, v198
	v_lshlrev_b32_e32 v100, 16, v199
	v_and_b32_e32 v101, 0xffff0000, v199
	v_pk_mul_f32 v[98:99], v[98:99], s[60:61] op_sel_hi:[1,0]
	v_pk_mul_f32 v[104:105], v[104:105], s[60:61] op_sel_hi:[1,0]
	v_pk_fma_f32 v[96:97], v[96:97], v[152:153], v[98:99]
	v_pk_mul_f32 v[98:99], v[106:107], s[60:61] op_sel_hi:[1,0]
	v_pk_mul_f32 v[100:101], v[100:101], s[60:61] op_sel_hi:[1,0]
	v_pk_fma_f32 v[94:95], v[94:95], v[154:155], v[104:105]
	v_pk_fma_f32 v[100:101], v[92:93], v[148:149], v[100:101]
	v_pk_fma_f32 v[92:93], v[90:91], v[150:151], v[98:99]
	v_cvt_pk_bf16_f32 v90, v94, v95
	v_cvt_pk_bf16_f32 v91, v96, v97
	v_cvt_pk_bf16_f32 v92, v92, v93
	v_cvt_pk_bf16_f32 v93, v100, v101
	global_store_dwordx4 v[102:103], v[90:93], off
	v_lshlrev_b32_e32 v94, 16, v200
	v_and_b32_e32 v95, 0xffff0000, v200
	v_lshlrev_b32_e32 v90, 16, v201
	v_and_b32_e32 v91, 0xffff0000, v201
	v_lshlrev_b32_e32 v96, 16, v202
	v_and_b32_e32 v97, 0xffff0000, v202
	v_lshlrev_b32_e32 v92, 16, v203
	v_and_b32_e32 v93, 0xffff0000, v203
	v_pk_mul_f32 v[90:91], v[90:91], s[60:61] op_sel_hi:[1,0]
	v_pk_mul_f32 v[94:95], v[94:95], s[60:61] op_sel_hi:[1,0]
	v_pk_fma_f32 v[88:89], v[88:89], v[144:145], v[90:91]
	v_pk_mul_f32 v[90:91], v[96:97], s[60:61] op_sel_hi:[1,0]
	v_pk_mul_f32 v[92:93], v[92:93], s[60:61] op_sel_hi:[1,0]
	v_pk_fma_f32 v[86:87], v[86:87], v[146:147], v[94:95]
	v_pk_fma_f32 v[92:93], v[84:85], v[140:141], v[92:93]
	v_pk_fma_f32 v[84:85], v[82:83], v[142:143], v[90:91]
	v_cvt_pk_bf16_f32 v82, v86, v87
	v_cvt_pk_bf16_f32 v83, v88, v89
	v_cvt_pk_bf16_f32 v84, v84, v85
	v_cvt_pk_bf16_f32 v85, v92, v93
	global_store_dwordx4 v[102:103], v[82:85], off offset:256
	s_nop 1
	v_or_b32_e32 v82, 48, v158
	v_ashrrev_i32_e32 v83, 31, v82
	v_lshlrev_b64 v[82:83], 12, v[82:83]
	v_lshl_add_u64 v[82:83], s[50:51], 0, v[82:83]
	v_lshl_add_u64 v[86:87], v[82:83], 0, v[160:161]
	v_lshlrev_b32_e32 v88, 16, v204
	v_and_b32_e32 v89, 0xffff0000, v204
	v_lshlrev_b32_e32 v82, 16, v205
	v_and_b32_e32 v83, 0xffff0000, v205
	v_lshlrev_b32_e32 v90, 16, v206
	v_and_b32_e32 v91, 0xffff0000, v206
	v_lshlrev_b32_e32 v84, 16, v207
	v_and_b32_e32 v85, 0xffff0000, v207
	v_pk_mul_f32 v[82:83], v[82:83], s[60:61] op_sel_hi:[1,0]
	v_pk_mul_f32 v[88:89], v[88:89], s[60:61] op_sel_hi:[1,0]
	v_pk_fma_f32 v[80:81], v[80:81], v[152:153], v[82:83]
	v_pk_mul_f32 v[82:83], v[90:91], s[60:61] op_sel_hi:[1,0]
	v_pk_mul_f32 v[84:85], v[84:85], s[60:61] op_sel_hi:[1,0]
	v_pk_fma_f32 v[78:79], v[78:79], v[154:155], v[88:89]
	v_pk_fma_f32 v[84:85], v[76:77], v[148:149], v[84:85]
	v_pk_fma_f32 v[76:77], v[74:75], v[150:151], v[82:83]
	v_cvt_pk_bf16_f32 v74, v78, v79
	v_cvt_pk_bf16_f32 v75, v80, v81
	v_cvt_pk_bf16_f32 v76, v76, v77
	v_cvt_pk_bf16_f32 v77, v84, v85
	global_store_dwordx4 v[86:87], v[74:77], off
	v_lshlrev_b32_e32 v78, 16, v218
	v_and_b32_e32 v79, 0xffff0000, v218
	v_lshlrev_b32_e32 v74, 16, v219
	v_and_b32_e32 v75, 0xffff0000, v219
	v_lshlrev_b32_e32 v80, 16, v220
	v_and_b32_e32 v81, 0xffff0000, v220
	v_lshlrev_b32_e32 v76, 16, v221
	v_and_b32_e32 v77, 0xffff0000, v221
	v_pk_mul_f32 v[74:75], v[74:75], s[60:61] op_sel_hi:[1,0]
	v_pk_mul_f32 v[78:79], v[78:79], s[60:61] op_sel_hi:[1,0]
	v_pk_fma_f32 v[72:73], v[72:73], v[144:145], v[74:75]
	v_pk_mul_f32 v[74:75], v[80:81], s[60:61] op_sel_hi:[1,0]
	v_pk_mul_f32 v[76:77], v[76:77], s[60:61] op_sel_hi:[1,0]
	v_pk_fma_f32 v[70:71], v[70:71], v[146:147], v[78:79]
	v_pk_fma_f32 v[76:77], v[68:69], v[140:141], v[76:77]
	v_pk_fma_f32 v[68:69], v[66:67], v[142:143], v[74:75]
	v_cvt_pk_bf16_f32 v67, v72, v73
	v_add_co_u32_e32 v72, vcc, s3, v156
	v_cvt_pk_bf16_f32 v66, v70, v71
	v_cvt_pk_bf16_f32 v68, v68, v69
	v_cvt_pk_bf16_f32 v69, v76, v77
	v_addc_co_u32_e32 v73, vcc, 0, v157, vcc
	global_store_dwordx4 v[86:87], v[66:69], off offset:256
	v_lshl_add_u32 v184, v158, 12, v160
	s_add_u32 s100, s50, 0x80000
	s_addc_u32 s101, s51, 0
	global_load_dwordx4 v[176:179], v184, s[100:101]
	global_load_dwordx4 v[180:183], v184, s[100:101] offset:256
	s_add_u32 s100, s100, 0x10000
	s_addc_u32 s101, s101, 0
	global_load_dwordx4 v[188:191], v184, s[100:101]
	global_load_dwordx4 v[192:195], v184, s[100:101] offset:256
	s_add_u32 s100, s100, 0x10000
	s_addc_u32 s101, s101, 0
	global_load_dwordx4 v[196:199], v184, s[100:101]
	global_load_dwordx4 v[200:203], v184, s[100:101] offset:256
	s_add_u32 s100, s100, 0x10000
	s_addc_u32 s101, s101, 0
	global_load_dwordx4 v[204:207], v184, s[100:101]
	global_load_dwordx4 v[218:221], v184, s[100:101] offset:256
	s_waitcnt vmcnt(0)
	s_mov_b32 s3, 0x90000
	v_lshl_add_u64 v[66:67], v[156:157], 0, s[18:19]
	s_mov_b64 s[18:19], 0x90000
	v_lshlrev_b32_e32 v74, 16, v176
	v_and_b32_e32 v75, 0xffff0000, v176
	v_lshlrev_b32_e32 v68, 16, v177
	v_and_b32_e32 v69, 0xffff0000, v177
	v_lshlrev_b32_e32 v76, 16, v178
	v_and_b32_e32 v77, 0xffff0000, v178
	v_lshlrev_b32_e32 v70, 16, v179
	v_and_b32_e32 v71, 0xffff0000, v179
	v_pk_mul_f32 v[68:69], v[68:69], s[60:61] op_sel_hi:[1,0]
	v_pk_mul_f32 v[74:75], v[74:75], s[60:61] op_sel_hi:[1,0]
	v_pk_fma_f32 v[64:65], v[64:65], v[152:153], v[68:69]
	v_pk_mul_f32 v[68:69], v[76:77], s[60:61] op_sel_hi:[1,0]
	v_pk_mul_f32 v[70:71], v[70:71], s[60:61] op_sel_hi:[1,0]
	v_pk_fma_f32 v[62:63], v[62:63], v[154:155], v[74:75]
	v_pk_fma_f32 v[70:71], v[60:61], v[148:149], v[70:71]
	v_pk_fma_f32 v[60:61], v[58:59], v[150:151], v[68:69]
	v_cvt_pk_bf16_f32 v58, v62, v63
	v_cvt_pk_bf16_f32 v59, v64, v65
	v_cvt_pk_bf16_f32 v60, v60, v61
	v_cvt_pk_bf16_f32 v61, v70, v71
	global_store_dwordx4 v[72:73], v[58:61], off
	v_lshlrev_b32_e32 v62, 16, v180
	v_and_b32_e32 v63, 0xffff0000, v180
	v_lshlrev_b32_e32 v58, 16, v181
	v_and_b32_e32 v59, 0xffff0000, v181
	v_lshlrev_b32_e32 v64, 16, v182
	v_and_b32_e32 v65, 0xffff0000, v182
	v_lshlrev_b32_e32 v60, 16, v183
	v_and_b32_e32 v61, 0xffff0000, v183
	v_pk_mul_f32 v[58:59], v[58:59], s[60:61] op_sel_hi:[1,0]
	v_pk_mul_f32 v[62:63], v[62:63], s[60:61] op_sel_hi:[1,0]
	v_pk_fma_f32 v[56:57], v[56:57], v[144:145], v[58:59]
	v_pk_mul_f32 v[58:59], v[64:65], s[60:61] op_sel_hi:[1,0]
	v_pk_mul_f32 v[60:61], v[60:61], s[60:61] op_sel_hi:[1,0]
	v_pk_fma_f32 v[54:55], v[54:55], v[146:147], v[62:63]
	v_pk_fma_f32 v[60:61], v[52:53], v[140:141], v[60:61]
	v_pk_fma_f32 v[52:53], v[50:51], v[142:143], v[58:59]
	v_cvt_pk_bf16_f32 v51, v56, v57
	v_add_co_u32_e32 v56, vcc, s3, v156
	v_cvt_pk_bf16_f32 v50, v54, v55
	v_cvt_pk_bf16_f32 v52, v52, v53
	v_cvt_pk_bf16_f32 v53, v60, v61
	v_addc_co_u32_e32 v57, vcc, 0, v157, vcc
	global_store_dwordx4 v[66:67], v[50:53], off offset:256
	s_nop 0
	s_mov_b32 s3, 0xa0000
	v_lshl_add_u64 v[50:51], v[156:157], 0, s[18:19]
	s_mov_b64 s[18:19], 0xa0000
	v_lshlrev_b32_e32 v58, 16, v188
	v_and_b32_e32 v59, 0xffff0000, v188
	v_lshlrev_b32_e32 v52, 16, v189
	v_and_b32_e32 v53, 0xffff0000, v189
	v_lshlrev_b32_e32 v60, 16, v190
	v_and_b32_e32 v61, 0xffff0000, v190
	v_lshlrev_b32_e32 v54, 16, v191
	v_and_b32_e32 v55, 0xffff0000, v191
	v_pk_mul_f32 v[52:53], v[52:53], s[60:61] op_sel_hi:[1,0]
	v_pk_mul_f32 v[58:59], v[58:59], s[60:61] op_sel_hi:[1,0]
	v_pk_fma_f32 v[48:49], v[48:49], v[152:153], v[52:53]
	v_pk_mul_f32 v[52:53], v[60:61], s[60:61] op_sel_hi:[1,0]
	v_pk_mul_f32 v[54:55], v[54:55], s[60:61] op_sel_hi:[1,0]
	v_pk_fma_f32 v[46:47], v[46:47], v[154:155], v[58:59]
	v_pk_fma_f32 v[54:55], v[44:45], v[148:149], v[54:55]
	v_pk_fma_f32 v[44:45], v[42:43], v[150:151], v[52:53]
	v_cvt_pk_bf16_f32 v42, v46, v47
	v_cvt_pk_bf16_f32 v43, v48, v49
	v_cvt_pk_bf16_f32 v44, v44, v45
	v_cvt_pk_bf16_f32 v45, v54, v55
	global_store_dwordx4 v[56:57], v[42:45], off
	v_lshlrev_b32_e32 v46, 16, v192
	v_and_b32_e32 v47, 0xffff0000, v192
	v_lshlrev_b32_e32 v42, 16, v193
	v_and_b32_e32 v43, 0xffff0000, v193
	v_lshlrev_b32_e32 v48, 16, v194
	v_and_b32_e32 v49, 0xffff0000, v194
	v_lshlrev_b32_e32 v44, 16, v195
	v_and_b32_e32 v45, 0xffff0000, v195
	v_pk_mul_f32 v[42:43], v[42:43], s[60:61] op_sel_hi:[1,0]
	v_pk_mul_f32 v[46:47], v[46:47], s[60:61] op_sel_hi:[1,0]
	v_pk_fma_f32 v[40:41], v[40:41], v[144:145], v[42:43]
	v_pk_mul_f32 v[42:43], v[48:49], s[60:61] op_sel_hi:[1,0]
	v_pk_mul_f32 v[44:45], v[44:45], s[60:61] op_sel_hi:[1,0]
	v_pk_fma_f32 v[38:39], v[38:39], v[146:147], v[46:47]
	v_pk_fma_f32 v[44:45], v[36:37], v[140:141], v[44:45]
	v_pk_fma_f32 v[36:37], v[34:35], v[142:143], v[42:43]
	v_cvt_pk_bf16_f32 v35, v40, v41
	v_add_co_u32_e32 v40, vcc, s3, v156
	v_cvt_pk_bf16_f32 v34, v38, v39
	v_cvt_pk_bf16_f32 v36, v36, v37
	v_cvt_pk_bf16_f32 v37, v44, v45
	v_addc_co_u32_e32 v41, vcc, 0, v157, vcc
	global_store_dwordx4 v[50:51], v[34:37], off offset:256
	s_nop 0
	s_mov_b32 s3, 0xb0000
	v_lshl_add_u64 v[34:35], v[156:157], 0, s[18:19]
	s_mov_b64 s[18:19], 0xb0000
	v_lshlrev_b32_e32 v42, 16, v196
	v_and_b32_e32 v43, 0xffff0000, v196
	v_lshlrev_b32_e32 v36, 16, v197
	v_and_b32_e32 v37, 0xffff0000, v197
	v_lshlrev_b32_e32 v44, 16, v198
	v_and_b32_e32 v45, 0xffff0000, v198
	v_lshlrev_b32_e32 v38, 16, v199
	v_and_b32_e32 v39, 0xffff0000, v199
	v_pk_mul_f32 v[36:37], v[36:37], s[60:61] op_sel_hi:[1,0]
	v_pk_mul_f32 v[42:43], v[42:43], s[60:61] op_sel_hi:[1,0]
	v_pk_fma_f32 v[32:33], v[32:33], v[152:153], v[36:37]
	v_pk_mul_f32 v[36:37], v[44:45], s[60:61] op_sel_hi:[1,0]
	v_pk_mul_f32 v[38:39], v[38:39], s[60:61] op_sel_hi:[1,0]
	v_pk_fma_f32 v[30:31], v[30:31], v[154:155], v[42:43]
	v_pk_fma_f32 v[38:39], v[28:29], v[148:149], v[38:39]
	v_pk_fma_f32 v[28:29], v[26:27], v[150:151], v[36:37]
	v_cvt_pk_bf16_f32 v26, v30, v31
	v_cvt_pk_bf16_f32 v27, v32, v33
	v_cvt_pk_bf16_f32 v28, v28, v29
	v_cvt_pk_bf16_f32 v29, v38, v39
	global_store_dwordx4 v[40:41], v[26:29], off
	v_lshlrev_b32_e32 v30, 16, v200
	v_and_b32_e32 v31, 0xffff0000, v200
	v_lshlrev_b32_e32 v26, 16, v201
	v_and_b32_e32 v27, 0xffff0000, v201
	v_lshlrev_b32_e32 v32, 16, v202
	v_and_b32_e32 v33, 0xffff0000, v202
	v_lshlrev_b32_e32 v28, 16, v203
	v_and_b32_e32 v29, 0xffff0000, v203
	v_pk_mul_f32 v[26:27], v[26:27], s[60:61] op_sel_hi:[1,0]
	v_pk_mul_f32 v[30:31], v[30:31], s[60:61] op_sel_hi:[1,0]
	v_pk_fma_f32 v[24:25], v[24:25], v[144:145], v[26:27]
	v_pk_mul_f32 v[26:27], v[32:33], s[60:61] op_sel_hi:[1,0]
	v_pk_mul_f32 v[28:29], v[28:29], s[60:61] op_sel_hi:[1,0]
	v_pk_fma_f32 v[22:23], v[22:23], v[146:147], v[30:31]
	v_pk_fma_f32 v[28:29], v[20:21], v[140:141], v[28:29]
	v_pk_fma_f32 v[20:21], v[18:19], v[142:143], v[26:27]
	v_cvt_pk_bf16_f32 v19, v24, v25
	v_add_co_u32_e32 v24, vcc, s3, v156
	v_cvt_pk_bf16_f32 v18, v22, v23
	v_cvt_pk_bf16_f32 v20, v20, v21
	v_cvt_pk_bf16_f32 v21, v28, v29
	v_addc_co_u32_e32 v25, vcc, 0, v157, vcc
	global_store_dwordx4 v[34:35], v[18:21], off offset:256
	s_nop 0
	s_andn2_b64 vcc, exec, s[0:1]
	v_lshl_add_u64 v[18:19], v[156:157], 0, s[18:19]
	s_mov_b64 s[18:19], -1
	v_lshlrev_b32_e32 v26, 16, v204
	v_and_b32_e32 v27, 0xffff0000, v204
	v_lshlrev_b32_e32 v20, 16, v205
	v_and_b32_e32 v21, 0xffff0000, v205
	v_lshlrev_b32_e32 v28, 16, v206
	v_and_b32_e32 v29, 0xffff0000, v206
	v_lshlrev_b32_e32 v22, 16, v207
	v_and_b32_e32 v23, 0xffff0000, v207
	v_pk_mul_f32 v[20:21], v[20:21], s[60:61] op_sel_hi:[1,0]
	v_pk_mul_f32 v[26:27], v[26:27], s[60:61] op_sel_hi:[1,0]
	v_pk_fma_f32 v[16:17], v[16:17], v[152:153], v[20:21]
	v_pk_mul_f32 v[20:21], v[28:29], s[60:61] op_sel_hi:[1,0]
	v_pk_mul_f32 v[22:23], v[22:23], s[60:61] op_sel_hi:[1,0]
	v_pk_fma_f32 v[14:15], v[14:15], v[154:155], v[26:27]
	v_pk_fma_f32 v[22:23], v[12:13], v[148:149], v[22:23]
	v_pk_fma_f32 v[12:13], v[10:11], v[150:151], v[20:21]
	v_cvt_pk_bf16_f32 v10, v14, v15
	v_cvt_pk_bf16_f32 v11, v16, v17
	v_cvt_pk_bf16_f32 v12, v12, v13
	v_cvt_pk_bf16_f32 v13, v22, v23
	global_store_dwordx4 v[24:25], v[10:13], off
	v_lshlrev_b32_e32 v14, 16, v218
	v_and_b32_e32 v15, 0xffff0000, v218
	v_lshlrev_b32_e32 v10, 16, v219
	v_and_b32_e32 v11, 0xffff0000, v219
	v_lshlrev_b32_e32 v16, 16, v220
	v_and_b32_e32 v17, 0xffff0000, v220
	v_lshlrev_b32_e32 v12, 16, v221
	v_and_b32_e32 v13, 0xffff0000, v221
	v_pk_mul_f32 v[10:11], v[10:11], s[60:61] op_sel_hi:[1,0]
	v_pk_mul_f32 v[14:15], v[14:15], s[60:61] op_sel_hi:[1,0]
	v_pk_fma_f32 v[8:9], v[8:9], v[144:145], v[10:11]
	v_pk_mul_f32 v[10:11], v[16:17], s[60:61] op_sel_hi:[1,0]
	v_pk_mul_f32 v[12:13], v[12:13], s[60:61] op_sel_hi:[1,0]
	v_pk_fma_f32 v[6:7], v[6:7], v[146:147], v[14:15]
	v_pk_fma_f32 v[12:13], v[4:5], v[140:141], v[12:13]
	v_pk_fma_f32 v[4:5], v[2:3], v[142:143], v[10:11]
	v_cvt_pk_bf16_f32 v2, v6, v7
	v_cvt_pk_bf16_f32 v3, v8, v9
	v_cvt_pk_bf16_f32 v4, v4, v5
	v_cvt_pk_bf16_f32 v5, v12, v13
	global_store_dwordx4 v[18:19], v[2:5], off offset:256
	s_cbranch_vccnz .LBB0_1038
	s_andn2_b64 vcc, exec, s[4:5]
	s_cbranch_vccnz .LBB0_1037
	s_barrier
	s_branch .LBB0_1037
